# final RMSNorm fused into layer-1 ff2 epilogue: 8 column tiles of a row panel in one round (XCD-pair mapping), row sum+arrival count accumulated in one f64 atomic word, phase 17 removed
# speedup vs baseline: 1.0113x; 1.0037x over previous
.LBB0_342:
	s_andn2_b64 vcc, exec, s[0:1]
	s_cbranch_vccnz .LBB0_349
	v_lshl_add_u32 v28, s84, 9, v154
	s_cmp_eq_u32 s12, 12
	s_cbranch_scc0 .Lfn_z_skip
	v_cmp_gt_u32_e32 vcc, 0x8000, v28
	s_and_saveexec_b64 s[42:43], vcc
	s_add_u32 s38, s24, 0x3c658000
	s_addc_u32 s39, s25, 0
	v_lshlrev_b32_e32 v2, 3, v28
	v_mov_b32_e32 v4, 0
	v_mov_b32_e32 v5, 0
	global_store_dwordx2 v2, v[4:5], s[38:39]
	s_mov_b64 exec, s[42:43]
.Lfn_z_skip:
	s_mov_b32 s0, 0x20000
	v_cmp_gt_i32_e32 vcc, s0, v28
	s_and_saveexec_b64 s[36:37], vcc
	s_cbranch_execz .LBB0_348
	s_add_u32 s38, s24, 0x25e88000
	s_addc_u32 s39, s25, 0
	s_add_u32 s42, s24, 0x2e088000
	s_addc_u32 s43, s25, 0
	s_add_u32 s44, s24, 0x38558000
	s_addc_u32 s45, s25, 0
	s_mov_b64 s[46:47], 0

.LBB0_368:
	s_lshl_b32 s20, s85, 3
	v_cvt_f32_u32_e32 v0, s20
	s_sub_i32 s29, 0, s20
	s_ashr_i32 s6, s6, 3
	s_add_i32 s6, s27, s6
	v_rcp_iflag_f32_e32 v0, v0
	s_abs_i32 s27, s6
	s_ashr_i32 s26, s6, 31
	v_mul_f32_e32 v0, 0x4f7ffffe, v0
	v_cvt_u32_f32_e32 v0, v0
	s_nop 0
	v_readfirstlane_b32 s31, v0
	s_mul_i32 s29, s29, s31
	s_mul_hi_u32 s29, s31, s29
	s_add_i32 s31, s31, s29
	s_mul_hi_u32 s29, s27, s31
	s_mul_i32 s31, s29, s20
	s_sub_i32 s27, s27, s31
	s_add_i32 s31, s29, 1
	s_sub_i32 s38, s27, s20
	s_cmp_ge_u32 s27, s20
	s_cselect_b32 s29, s31, s29
	s_cselect_b32 s27, s38, s27
	s_add_i32 s31, s29, 1
	s_cmp_ge_u32 s27, s20
	s_cselect_b32 s27, s31, s29
	s_xor_b32 s27, s27, s26
	s_sub_i32 s26, s27, s26
	s_lshl_b32 s27, s26, 3
	s_sub_i32 s29, s92, s27
	s_min_i32 s29, s29, 8
	s_abs_i32 s31, s29
	v_cvt_f32_u32_e32 v0, s31
	s_sub_i32 s38, 0, s31
	s_mul_i32 s26, s26, s20
	s_sub_i32 s20, s6, s26
	v_rcp_iflag_f32_e32 v0, v0
	s_abs_i32 s26, s20
	s_xor_b32 s6, s20, s29
	s_ashr_i32 s6, s6, 31
	v_mul_f32_e32 v0, 0x4f7ffffe, v0
	v_cvt_u32_f32_e32 v0, v0
	s_nop 0
	v_readfirstlane_b32 s39, v0
	s_mul_i32 s38, s38, s39
	s_mul_hi_u32 s38, s39, s38
	s_add_i32 s39, s39, s38
	s_mul_hi_u32 s38, s26, s39
	v_cvt_f32_ubyte0_e32 v0, s88
	s_mul_i32 s39, s38, s31
	v_rcp_iflag_f32_e32 v0, v0
	s_sub_i32 s26, s26, s39
	s_add_i32 s39, s38, 1
	s_sub_i32 s42, s26, s31
	s_cmp_ge_u32 s26, s31
	s_cselect_b32 s38, s39, s38
	v_mul_f32_e32 v0, 0x4f7ffffe, v0
	s_cselect_b32 s26, s42, s26
	s_add_i32 s39, s38, 1
	v_cvt_u32_f32_e32 v0, v0
	s_cmp_ge_u32 s26, s31
	s_cselect_b32 s26, s39, s38
	s_xor_b32 s26, s26, s6
	s_sub_i32 s6, s26, s6
	v_readfirstlane_b32 s31, v0
	v_cvt_f32_u32_e32 v0, s85
	s_mul_i32 s26, s6, s29
	s_sub_i32 s29, 0, s88
	s_mul_i32 s29, s29, s31
	s_sub_i32 s20, s20, s26
	s_mul_hi_u32 s29, s31, s29
	s_add_i32 s20, s20, s27
	s_abs_i32 s27, s2
	s_add_i32 s31, s31, s29
	v_rcp_iflag_f32_e32 v0, v0
	s_mul_hi_u32 s29, s27, s31
	s_mul_i32 s31, s29, s88
	s_sub_i32 s27, s27, s31
	s_ashr_i32 s26, s2, 31
	s_add_i32 s31, s29, 1
	s_sub_i32 s38, s27, s88
	v_mul_f32_e32 v0, 0x4f7ffffe, v0
	s_cmp_ge_u32 s27, s88
	v_cvt_u32_f32_e32 v0, v0
	s_cselect_b32 s29, s31, s29
	s_cselect_b32 s27, s38, s27
	s_add_i32 s31, s29, 1
	s_cmp_ge_u32 s27, s88
	s_cselect_b32 s27, s31, s29
	s_sub_i32 s31, 0, s85
	v_readfirstlane_b32 s38, v0
	s_xor_b32 s27, s27, s26
	s_mul_i32 s31, s31, s38
	s_sub_i32 s26, s27, s26
	s_mul_hi_u32 s31, s38, s31
	s_abs_i32 s29, s26
	s_add_i32 s38, s38, s31
	s_mul_hi_u32 s31, s29, s38
	s_mul_i32 s38, s31, s85
	s_sub_i32 s29, s29, s38
	s_ashr_i32 s27, s26, 31
	s_add_i32 s38, s31, 1
	s_sub_i32 s39, s29, s85
	s_cmp_ge_u32 s29, s85
	s_cselect_b32 s31, s38, s31
	s_cselect_b32 s29, s39, s29
	s_add_i32 s38, s31, 1
	s_cmp_ge_u32 s29, s85
	s_cselect_b32 s29, s38, s31
	s_xor_b32 s29, s29, s27
	s_sub_i32 s27, s29, s27
	s_add_i32 s29, s27, s89
	s_mul_i32 s27, s27, s85
	s_sub_i32 s31, s26, s27
	s_mul_i32 s26, s26, s88
	s_sub_i32 s2, s2, s26
	s_mul_i32 s2, s90, s2
	s_lshl_b32 s2, s2, 6
	s_and_b64 s[26:27], s[36:37], exec
	v_readlane_b32 s38, v254, 58
	s_cselect_b32 s77, s20, s29
	s_cselect_b32 s76, s6, s31
	s_cselect_b32 s42, 0, s2
	s_cselect_b32 s6, s93, s90
	v_readlane_b32 s39, v254, 59
	s_cmp_eq_u32 s12, 16
	s_cbranch_scc0 .Lfn_rm0
	s_and_b32 s26, s84, 7
	s_lshr_b32 s27, s26, 1
	s_lshl_b32 s27, s27, 5
	s_and_b32 s77, s77, 7
	s_add_i32 s77, s77, s27
	s_and_b32 s26, s26, 1
	s_lshl_b32 s26, s26, 2
	s_and_b32 s76, s76, 3
	s_add_i32 s76, s76, s26
.Lfn_rm0:
.LBB0_369:
	s_and_b64 vcc, exec, s[0:1]
	s_cbranch_vccnz .LBB0_579
	s_waitcnt lgkmcnt(0)
	v_bfe_i32 v3, v154, 27, 1
	v_lshlrev_b32_e32 v0, 4, v154
	v_lshrrev_b32_e32 v3, 22, v3
	v_add_u32_e32 v3, v0, v3
	v_and_b32_e32 v3, 0xfffffc00, v3
	v_sub_u32_e32 v3, v0, v3
	v_ashrrev_i32_e32 v2, 31, v154
	v_lshrrev_b32_e32 v4, 4, v3
	v_lshrrev_b32_e32 v2, 26, v2
	v_bitop3_b32 v3, v4, v3, 32 bitop3:0x6c
	v_add_u32_e32 v2, v154, v2
	v_ashrrev_i32_e32 v5, 31, v3
	v_ashrrev_i32_e32 v2, 6, v2
	v_lshrrev_b32_e32 v5, 26, v5
	v_lshlrev_b32_e32 v4, 3, v2
	v_add_u32_e32 v5, v3, v5
	v_and_b32_e32 v4, -16, v4
	v_ashrrev_i32_e32 v6, 6, v5
	v_lshlrev_b32_e32 v2, 5, v2
	v_add_u32_e32 v4, v6, v4
	s_waitcnt vmcnt(0)
	v_and_b32_e32 v14, 32, v2
	v_and_b32_e32 v2, 0xc0, v5
	v_sub_u32_e32 v2, v3, v2
	v_lshlrev_b32_e32 v3, 1, v4
	v_lshrrev_b32_e32 v5, 2, v4
	v_ashrrev_i16_sdwa v2, v208, sext(v2) dst_sel:DWORD dst_unused:UNUSED_PAD src0_sel:DWORD src1_sel:BYTE_0
	v_and_b32_e32 v5, 4, v5
	v_and_b32_e32 v6, 3, v6
	v_and_b32_e32 v3, 0x7fffffd8, v3
	v_bfe_i32 v15, v2, 0, 16
	v_or3_b32 v3, v6, v5, v3
	v_add_u32_e32 v2, v14, v15
	v_mul_lo_u32 v16, s3, v4
	v_mul_lo_u32 v3, s3, v3
	v_add_u32_e32 v0, 0x2000, v0
	v_add_lshl_u32 v156, v16, v2, 1
	v_add_lshl_u32 v158, v3, v2, 1
	v_ashrrev_i32_e32 v2, 31, v0
	v_lshrrev_b32_e32 v2, 22, v2
	v_add_u32_e32 v2, v0, v2
	v_ashrrev_i32_e32 v2, 10, v2
	v_mul_i32_i24_e32 v3, 0x400, v2
	v_sub_u32_e32 v0, v0, v3
	v_lshrrev_b32_e32 v3, 4, v0
	v_bitop3_b32 v0, v3, v0, 32 bitop3:0x6c
	v_ashrrev_i32_e32 v4, 31, v0
	v_lshrrev_b32_e32 v4, 26, v4
	v_lshlrev_b32_e32 v3, 3, v2
	v_add_u32_e32 v4, v0, v4
	v_and_b32_e32 v3, -16, v3
	v_ashrrev_i32_e32 v5, 6, v4
	v_lshlrev_b32_e32 v2, 5, v2
	v_add_u32_e32 v3, v5, v3
	v_and_b32_e32 v17, 32, v2
	v_and_b32_e32 v2, 0xc0, v4
	v_sub_u32_e32 v0, v0, v2
	v_lshlrev_b32_e32 v2, 1, v3
	v_lshrrev_b32_e32 v4, 2, v3
	v_and_b32_e32 v4, 4, v4
	v_and_b32_e32 v5, 3, v5
	v_and_b32_e32 v2, 0x7fffffd8, v2
	s_ashr_i32 s0, s56, 6
	v_or3_b32 v2, v5, v4, v2
	s_lshl_b32 s96, s3, 9
	s_ashr_i32 s43, s42, 31
	v_mul_lo_u32 v19, s3, v3
	v_mul_lo_u32 v2, s3, v2
	s_ashr_i32 s1, s56, 8
	s_lshl_b32 s20, s3, 8
	s_lshl_b32 s95, s3, 6
	s_lshl_b32 s97, s0, 10
	s_lshl_b64 s[2:3], s[42:43], 1
	s_mul_i32 s31, s96, s76
	s_mul_hi_i32 s29, s96, s76
	s_add_u32 s31, s18, s31
	s_addc_u32 s29, s19, s29
	s_add_u32 s44, s31, s2
	s_addc_u32 s45, s29, s3
	s_add_i32 s98, s97, 0
	s_add_i32 m0, s98, 0x10000
	v_ashrrev_i16_sdwa v0, v208, sext(v0) dst_sel:DWORD dst_unused:UNUSED_PAD src0_sel:DWORD src1_sel:BYTE_0
	s_mul_i32 s27, s96, s77
	global_load_lds_dwordx4 v158, s[44:45]
	s_add_i32 m0, s98, 0x12000
	v_bfe_i32 v18, v0, 0, 16
	s_mul_hi_i32 s26, s96, s77
	s_add_u32 s27, s40, s27
	v_add_u32_e32 v0, v17, v18
	s_addc_u32 s26, s41, s26
	v_add_lshl_u32 v162, v2, v0, 1
	s_add_u32 s46, s27, s2
	global_load_lds_dwordx4 v162, s[44:45]
	s_addc_u32 s47, s26, s3
	s_mov_b32 m0, s98
	s_add_i32 s99, s98, 0x2000
	v_add_lshl_u32 v160, v19, v0, 1
	global_load_lds_dwordx4 v156, s[46:47]
	s_mov_b32 m0, s99
	s_add_u32 s2, s44, s95
	global_load_lds_dwordx4 v160, s[46:47]
	s_addc_u32 s3, s45, 0
	s_add_i32 m0, s98, 0x14000
	v_mov_b32_e32 v159, v1
	v_mov_b32_e32 v163, v1
	global_load_lds_dwordx4 v158, s[2:3]
	s_add_i32 m0, s98, 0x16000
	v_lshl_add_u64 v[10:11], s[2:3], 0, v[158:159]
	v_lshl_add_u64 v[12:13], s[2:3], 0, v[162:163]
	global_load_lds_dwordx4 v162, s[2:3]
	s_add_u32 s2, s46, s20
	s_addc_u32 s3, s47, 0
	s_add_i32 s94, s98, 0x4000
	s_mov_b32 m0, s94
	s_add_i32 s65, s98, 0x6000
	global_load_lds_dwordx4 v156, s[2:3]
	s_mov_b32 m0, s65
	v_mov_b32_e32 v157, v1
	global_load_lds_dwordx4 v160, s[2:3]
	v_mov_b32_e32 v161, v1
	v_writelane_b32 v252, s60, 25
	v_lshl_add_u64 v[2:3], s[44:45], 0, v[158:159]
	v_lshl_add_u64 v[4:5], s[44:45], 0, v[162:163]
	v_lshl_add_u64 v[6:7], s[46:47], 0, v[156:157]
	v_lshl_add_u64 v[8:9], s[46:47], 0, v[160:161]
	s_cmp_lg_u32 s1, 1
	v_writelane_b32 v252, s61, 26
	s_cbranch_scc1 .LBB0_372
	s_barrier

.LBB0_381:
	s_ashr_i32 s3, s3, 3
	s_add_i32 s3, s57, s3
	s_abs_i32 s57, s3
	s_mul_hi_u32 s70, s57, s78
	s_mul_i32 s71, s70, s2
	s_sub_i32 s57, s57, s71
	s_ashr_i32 s7, s3, 31
	s_add_i32 s71, s70, 1
	s_sub_i32 s72, s57, s2
	s_cmp_ge_u32 s57, s2
	s_cselect_b32 s70, s71, s70
	s_cselect_b32 s57, s72, s57
	s_add_i32 s71, s70, 1
	s_cmp_ge_u32 s57, s2
	s_cselect_b32 s57, s71, s70
	s_xor_b32 s57, s57, s7
	s_sub_i32 s7, s57, s7
	s_lshl_b32 s57, s7, 3
	s_sub_i32 s70, s92, s57
	s_min_i32 s70, s70, 8
	s_abs_i32 s71, s70
	v_cvt_f32_u32_e32 v0, s71
	s_sub_i32 s73, 0, s71
	s_mul_i32 s7, s7, s2
	s_sub_i32 s3, s3, s7
	v_rcp_iflag_f32_e32 v0, v0
	s_abs_i32 s7, s3
	s_xor_b32 s72, s3, s70
	s_ashr_i32 s72, s72, 31
	v_mul_f32_e32 v0, 0x4f7ffffe, v0
	v_cvt_u32_f32_e32 v0, v0
	s_nop 0
	v_readfirstlane_b32 s74, v0
	s_mul_i32 s73, s73, s74
	s_mul_hi_u32 s73, s74, s73
	s_add_i32 s74, s74, s73
	s_mul_hi_u32 s73, s7, s74
	s_mul_i32 s74, s73, s71
	s_sub_i32 s7, s7, s74
	s_add_i32 s74, s73, 1
	s_sub_i32 s75, s7, s71
	s_cmp_ge_u32 s7, s71
	s_cselect_b32 s73, s74, s73
	s_cselect_b32 s7, s75, s7
	s_add_i32 s74, s73, 1
	s_cmp_ge_u32 s7, s71
	s_cselect_b32 s7, s74, s73
	s_xor_b32 s7, s7, s72
	s_sub_i32 s7, s7, s72
	s_mul_i32 s70, s7, s70
	s_sub_i32 s3, s3, s70
	s_abs_i32 s70, s43
	s_mul_hi_u32 s71, s70, s30
	s_mul_i32 s72, s71, s88
	s_sub_i32 s70, s70, s72
	s_add_i32 s3, s3, s57
	s_ashr_i32 s57, s43, 31
	s_add_i32 s72, s71, 1
	s_sub_i32 s73, s70, s88
	s_cmp_ge_u32 s70, s88
	s_cselect_b32 s71, s72, s71
	s_cselect_b32 s70, s73, s70
	s_add_i32 s72, s71, 1
	s_cmp_ge_u32 s70, s88
	s_cselect_b32 s70, s72, s71
	s_xor_b32 s70, s70, s57
	s_sub_i32 s57, s70, s57
	s_abs_i32 s71, s57
	s_mul_hi_u32 s72, s71, s31
	s_mul_i32 s73, s72, s85
	s_sub_i32 s71, s71, s73
	s_ashr_i32 s70, s57, 31
	s_add_i32 s73, s72, 1
	s_sub_i32 s74, s71, s85
	s_cmp_ge_u32 s71, s85
	s_cselect_b32 s72, s73, s72
	s_cselect_b32 s71, s74, s71
	s_add_i32 s73, s72, 1
	s_cmp_ge_u32 s71, s85
	s_cselect_b32 s71, s73, s72
	s_xor_b32 s71, s71, s70
	s_sub_i32 s70, s71, s70
	s_add_i32 s71, s70, s89
	s_mul_i32 s70, s70, s85
	s_sub_i32 s70, s57, s70
	s_mul_i32 s57, s57, s88
	s_sub_i32 s43, s43, s57
	v_readlane_b32 s57, v252, 9
	s_mul_i32 s43, s57, s43
	s_and_b64 s[0:1], s[0:1], exec
	s_cselect_b32 s57, s3, s71
	s_cselect_b32 s7, s7, s70
	s_cselect_b32 s70, 0, s43
	s_cselect_b32 s3, s93, s90
	s_cmp_eq_u32 s12, 16
	s_cbranch_scc0 .Lfn_rm1
	s_and_b32 s71, s84, 7
	s_lshr_b32 s72, s71, 1
	s_lshl_b32 s72, s72, 2
	s_add_i32 s72, s72, s52
	s_lshl_b32 s72, s72, 3
	s_and_b32 s57, s57, 7
	s_add_i32 s57, s57, s72
	s_and_b32 s71, s71, 1
	s_lshl_b32 s71, s71, 2
	s_and_b32 s7, s7, 3
	s_add_i32 s7, s7, s71
.Lfn_rm1:
.LBB0_382:
	v_cndmask_b32_e64 v0, 0, 1, s[48:49]
	v_cmp_ne_u32_e64 s[0:1], 1, v0
	s_andn2_b64 vcc, exec, s[48:49]
	s_mov_b64 s[72:73], s[46:47]
	s_cbranch_vccnz .LBB0_400
	s_mul_i32 s48, s96, s57
	s_mul_hi_i32 s43, s96, s57
	s_add_u32 s72, s40, s48
	s_addc_u32 s43, s41, s43
	s_ashr_i32 s71, s70, 31
	s_lshl_b64 s[48:49], s[70:71], 1
	s_add_u32 s72, s72, s48
	s_addc_u32 s73, s43, s49
	s_and_b64 vcc, exec, s[0:1]
	s_mov_b64 s[74:75], s[44:45]
	s_cbranch_vccz .LBB0_401

.Lres_noaout:
	s_cmp_eq_u32 s12, 16
	s_cbranch_scc0 .Lres_noaout_old
	s_sub_u32 s0, s58, 0x20800
	s_subb_u32 s1, s59, 0
	v_lshl_add_u64 v[198:199], v[176:177], 3, s[0:1]
	s_mov_b32 s44, 0
	s_mov_b32 s45, 0x42700000
	global_load_dwordx4 v[230:233], v[246:247], off
	global_load_dwordx4 v[234:237], v[246:247], off offset:16
	global_load_dwordx4 v[238:241], v[246:247], off offset:128
	global_load_dwordx4 v[242:245], v[246:247], off offset:144
	s_mov_b64 s[42:43], 0x20000
	v_lshl_add_u64 v[180:181], v[246:247], 0, s[42:43]
	global_load_dwordx4 v[146:149], v[180:181], off
	global_load_dwordx4 v[150:153], v[180:181], off offset:16
	global_load_dwordx4 v[176:179], v[180:181], off offset:128
	global_load_dwordx4 v[202:205], v[180:181], off offset:144
	s_mov_b64 s[42:43], 0x40000
	v_lshl_add_u64 v[180:181], v[246:247], 0, s[42:43]
	global_load_dwordx4 v[182:185], v[180:181], off
	global_load_dwordx4 v[186:189], v[180:181], off offset:16
	global_load_dwordx4 v[190:193], v[180:181], off offset:128
	global_load_dwordx4 v[194:197], v[180:181], off offset:144
	s_waitcnt vmcnt(8)
	v_pk_fma_f32 v[126:127], v[126:127], v[142:143], v[230:231]
	v_pk_fma_f32 v[128:129], v[128:129], v[144:145], v[232:233]
	v_pk_fma_f32 v[122:123], v[122:123], v[138:139], v[234:235]
	v_pk_fma_f32 v[124:125], v[124:125], v[140:141], v[236:237]
	v_pk_fma_f32 v[118:119], v[118:119], v[134:135], v[238:239]
	v_pk_fma_f32 v[120:121], v[120:121], v[136:137], v[240:241]
	v_pk_fma_f32 v[114:115], v[114:115], v[130:131], v[242:243]
	v_pk_fma_f32 v[116:117], v[116:117], v[132:133], v[244:245]
	v_mul_f32_e32 v250, v126, v126
	v_mul_f32_e32 v251, v118, v118
	v_fmac_f32_e32 v250, v127, v127
	v_fmac_f32_e32 v251, v119, v119
	v_fmac_f32_e32 v250, v128, v128
	v_fmac_f32_e32 v251, v120, v120
	v_fmac_f32_e32 v250, v129, v129
	v_fmac_f32_e32 v251, v121, v121
	v_fmac_f32_e32 v250, v122, v122
	v_fmac_f32_e32 v251, v114, v114
	v_fmac_f32_e32 v250, v123, v123
	v_fmac_f32_e32 v251, v115, v115
	v_fmac_f32_e32 v250, v124, v124
	v_fmac_f32_e32 v251, v116, v116
	v_fmac_f32_e32 v250, v125, v125
	v_fmac_f32_e32 v251, v117, v117
	s_mov_b64 s[42:43], 0x60000
	v_lshl_add_u64 v[180:181], v[246:247], 0, s[42:43]
	global_load_dwordx4 v[230:233], v[180:181], off
	global_load_dwordx4 v[234:237], v[180:181], off offset:16
	global_load_dwordx4 v[238:241], v[180:181], off offset:128
	global_load_dwordx4 v[242:245], v[180:181], off offset:144
	v_add_f32_e32 v250, v250, v251
	ds_bpermute_b32 v251, v200, v250
	s_waitcnt lgkmcnt(0)
	v_add_f32_e32 v250, v250, v251
	ds_bpermute_b32 v251, v201, v250
	s_waitcnt lgkmcnt(0)
	v_add_f32_e32 v250, v250, v251
	v_cvt_f64_f32_e32 v[180:181], v250
	s_nop 0
	v_add_f64 v[180:181], v[180:181], s[44:45]
	s_and_saveexec_b64 s[42:43], s[38:39]
	global_atomic_add_f64 v[198:199], v[180:181], off
	s_mov_b64 exec, s[42:43]
	s_nop 1
	s_waitcnt vmcnt(9)
	v_pk_fma_f32 v[110:111], v[110:111], v[142:143], v[146:147]
	v_pk_fma_f32 v[112:113], v[112:113], v[144:145], v[148:149]
	v_pk_fma_f32 v[106:107], v[106:107], v[138:139], v[150:151]
	v_pk_fma_f32 v[108:109], v[108:109], v[140:141], v[152:153]
	v_pk_fma_f32 v[102:103], v[102:103], v[134:135], v[176:177]
	v_pk_fma_f32 v[104:105], v[104:105], v[136:137], v[178:179]
	v_pk_fma_f32 v[98:99], v[98:99], v[130:131], v[202:203]
	v_pk_fma_f32 v[100:101], v[100:101], v[132:133], v[204:205]
	v_mul_f32_e32 v250, v110, v110
	v_mul_f32_e32 v251, v102, v102
	v_fmac_f32_e32 v250, v111, v111
	v_fmac_f32_e32 v251, v103, v103
	v_fmac_f32_e32 v250, v112, v112
	v_fmac_f32_e32 v251, v104, v104
	v_fmac_f32_e32 v250, v113, v113
	v_fmac_f32_e32 v251, v105, v105
	v_fmac_f32_e32 v250, v106, v106
	v_fmac_f32_e32 v251, v98, v98
	v_fmac_f32_e32 v250, v107, v107
	v_fmac_f32_e32 v251, v99, v99
	v_fmac_f32_e32 v250, v108, v108
	v_fmac_f32_e32 v251, v100, v100
	v_fmac_f32_e32 v250, v109, v109
	v_fmac_f32_e32 v251, v101, v101
	s_mov_b64 s[42:43], 0x100000
	v_lshl_add_u64 v[180:181], v[246:247], 0, s[42:43]
	global_load_dwordx4 v[146:149], v[180:181], off
	global_load_dwordx4 v[150:153], v[180:181], off offset:16
	global_load_dwordx4 v[176:179], v[180:181], off offset:128
	global_load_dwordx4 v[202:205], v[180:181], off offset:144
	v_add_f32_e32 v250, v250, v251
	ds_bpermute_b32 v251, v200, v250
	s_waitcnt lgkmcnt(0)
	v_add_f32_e32 v250, v250, v251
	ds_bpermute_b32 v251, v201, v250
	s_waitcnt lgkmcnt(0)
	v_add_f32_e32 v250, v250, v251
	v_cvt_f64_f32_e32 v[180:181], v250
	s_nop 0
	v_add_f64 v[180:181], v[180:181], s[44:45]
	s_and_saveexec_b64 s[42:43], s[38:39]
	global_atomic_add_f64 v[198:199], v[180:181], off offset:128
	s_mov_b64 exec, s[42:43]
	s_nop 1
	s_waitcnt vmcnt(10)
	v_pk_fma_f32 v[94:95], v[94:95], v[142:143], v[182:183]
	v_pk_fma_f32 v[96:97], v[96:97], v[144:145], v[184:185]
	v_pk_fma_f32 v[90:91], v[90:91], v[138:139], v[186:187]
	v_pk_fma_f32 v[92:93], v[92:93], v[140:141], v[188:189]
	v_pk_fma_f32 v[86:87], v[86:87], v[134:135], v[190:191]
	v_pk_fma_f32 v[88:89], v[88:89], v[136:137], v[192:193]
	v_pk_fma_f32 v[82:83], v[82:83], v[130:131], v[194:195]
	v_pk_fma_f32 v[84:85], v[84:85], v[132:133], v[196:197]
	v_mul_f32_e32 v250, v94, v94
	v_mul_f32_e32 v251, v86, v86
	v_fmac_f32_e32 v250, v95, v95
	v_fmac_f32_e32 v251, v87, v87
	v_fmac_f32_e32 v250, v96, v96
	v_fmac_f32_e32 v251, v88, v88
	v_fmac_f32_e32 v250, v97, v97
	v_fmac_f32_e32 v251, v89, v89
	v_fmac_f32_e32 v250, v90, v90
	v_fmac_f32_e32 v251, v82, v82
	v_fmac_f32_e32 v250, v91, v91
	v_fmac_f32_e32 v251, v83, v83
	v_fmac_f32_e32 v250, v92, v92
	v_fmac_f32_e32 v251, v84, v84
	v_fmac_f32_e32 v250, v93, v93
	v_fmac_f32_e32 v251, v85, v85
	s_mov_b64 s[42:43], 0x120000
	v_lshl_add_u64 v[180:181], v[246:247], 0, s[42:43]
	global_load_dwordx4 v[182:185], v[180:181], off
	global_load_dwordx4 v[186:189], v[180:181], off offset:16
	global_load_dwordx4 v[190:193], v[180:181], off offset:128
	global_load_dwordx4 v[194:197], v[180:181], off offset:144
	v_add_f32_e32 v250, v250, v251
	ds_bpermute_b32 v251, v200, v250
	s_waitcnt lgkmcnt(0)
	v_add_f32_e32 v250, v250, v251
	ds_bpermute_b32 v251, v201, v250
	s_waitcnt lgkmcnt(0)
	v_add_f32_e32 v250, v250, v251
	v_cvt_f64_f32_e32 v[180:181], v250
	s_nop 0
	v_add_f64 v[180:181], v[180:181], s[44:45]
	s_and_saveexec_b64 s[42:43], s[38:39]
	global_atomic_add_f64 v[198:199], v[180:181], off offset:256
	s_mov_b64 exec, s[42:43]
	s_nop 1
	s_waitcnt vmcnt(11)
	v_pk_fma_f32 v[78:79], v[78:79], v[142:143], v[230:231]
	v_pk_fma_f32 v[80:81], v[80:81], v[144:145], v[232:233]
	v_pk_fma_f32 v[74:75], v[74:75], v[138:139], v[234:235]
	v_pk_fma_f32 v[76:77], v[76:77], v[140:141], v[236:237]
	v_pk_fma_f32 v[70:71], v[70:71], v[134:135], v[238:239]
	v_pk_fma_f32 v[72:73], v[72:73], v[136:137], v[240:241]
	v_pk_fma_f32 v[66:67], v[66:67], v[130:131], v[242:243]
	v_pk_fma_f32 v[68:69], v[68:69], v[132:133], v[244:245]
	v_mul_f32_e32 v250, v78, v78
	v_mul_f32_e32 v251, v70, v70
	v_fmac_f32_e32 v250, v79, v79
	v_fmac_f32_e32 v251, v71, v71
	v_fmac_f32_e32 v250, v80, v80
	v_fmac_f32_e32 v251, v72, v72
	v_fmac_f32_e32 v250, v81, v81
	v_fmac_f32_e32 v251, v73, v73
	v_fmac_f32_e32 v250, v74, v74
	v_fmac_f32_e32 v251, v66, v66
	v_fmac_f32_e32 v250, v75, v75
	v_fmac_f32_e32 v251, v67, v67
	v_fmac_f32_e32 v250, v76, v76
	v_fmac_f32_e32 v251, v68, v68
	v_fmac_f32_e32 v250, v77, v77
	v_fmac_f32_e32 v251, v69, v69
	s_mov_b64 s[42:43], 0x140000
	v_lshl_add_u64 v[180:181], v[246:247], 0, s[42:43]
	global_load_dwordx4 v[230:233], v[180:181], off
	global_load_dwordx4 v[234:237], v[180:181], off offset:16
	global_load_dwordx4 v[238:241], v[180:181], off offset:128
	global_load_dwordx4 v[242:245], v[180:181], off offset:144
	v_add_f32_e32 v250, v250, v251
	ds_bpermute_b32 v251, v200, v250
	s_waitcnt lgkmcnt(0)
	v_add_f32_e32 v250, v250, v251
	ds_bpermute_b32 v251, v201, v250
	s_waitcnt lgkmcnt(0)
	v_add_f32_e32 v250, v250, v251
	v_cvt_f64_f32_e32 v[180:181], v250
	s_nop 0
	v_add_f64 v[180:181], v[180:181], s[44:45]
	s_and_saveexec_b64 s[42:43], s[38:39]
	global_atomic_add_f64 v[198:199], v[180:181], off offset:384
	s_mov_b64 exec, s[42:43]
	s_nop 1
	s_waitcnt vmcnt(11)
	v_pk_fma_f32 v[62:63], v[62:63], v[142:143], v[146:147]
	v_pk_fma_f32 v[64:65], v[64:65], v[144:145], v[148:149]
	v_pk_fma_f32 v[58:59], v[58:59], v[138:139], v[150:151]
	v_pk_fma_f32 v[60:61], v[60:61], v[140:141], v[152:153]
	v_pk_fma_f32 v[54:55], v[54:55], v[134:135], v[176:177]
	v_pk_fma_f32 v[56:57], v[56:57], v[136:137], v[178:179]
	v_pk_fma_f32 v[50:51], v[50:51], v[130:131], v[202:203]
	v_pk_fma_f32 v[52:53], v[52:53], v[132:133], v[204:205]
	v_mul_f32_e32 v250, v62, v62
	v_mul_f32_e32 v251, v54, v54
	v_fmac_f32_e32 v250, v63, v63
	v_fmac_f32_e32 v251, v55, v55
	v_fmac_f32_e32 v250, v64, v64
	v_fmac_f32_e32 v251, v56, v56
	v_fmac_f32_e32 v250, v65, v65
	v_fmac_f32_e32 v251, v57, v57
	v_fmac_f32_e32 v250, v58, v58
	v_fmac_f32_e32 v251, v50, v50
	v_fmac_f32_e32 v250, v59, v59
	v_fmac_f32_e32 v251, v51, v51
	v_fmac_f32_e32 v250, v60, v60
	v_fmac_f32_e32 v251, v52, v52
	v_fmac_f32_e32 v250, v61, v61
	v_fmac_f32_e32 v251, v53, v53
	s_mov_b64 s[42:43], 0x160000
	v_lshl_add_u64 v[180:181], v[246:247], 0, s[42:43]
	global_load_dwordx4 v[146:149], v[180:181], off
	global_load_dwordx4 v[150:153], v[180:181], off offset:16
	global_load_dwordx4 v[176:179], v[180:181], off offset:128
	global_load_dwordx4 v[202:205], v[180:181], off offset:144
	v_add_f32_e32 v250, v250, v251
	ds_bpermute_b32 v251, v200, v250
	s_waitcnt lgkmcnt(0)
	v_add_f32_e32 v250, v250, v251
	ds_bpermute_b32 v251, v201, v250
	s_waitcnt lgkmcnt(0)
	v_add_f32_e32 v250, v250, v251
	v_cvt_f64_f32_e32 v[180:181], v250
	s_nop 0
	v_add_f64 v[180:181], v[180:181], s[44:45]
	s_and_saveexec_b64 s[42:43], s[38:39]
	global_atomic_add_f64 v[198:199], v[180:181], off offset:1024
	s_mov_b64 exec, s[42:43]
	s_nop 1
	s_waitcnt vmcnt(11)
	v_pk_fma_f32 v[46:47], v[46:47], v[142:143], v[182:183]
	v_pk_fma_f32 v[48:49], v[48:49], v[144:145], v[184:185]
	v_pk_fma_f32 v[42:43], v[42:43], v[138:139], v[186:187]
	v_pk_fma_f32 v[44:45], v[44:45], v[140:141], v[188:189]
	v_pk_fma_f32 v[38:39], v[38:39], v[134:135], v[190:191]
	v_pk_fma_f32 v[40:41], v[40:41], v[136:137], v[192:193]
	v_pk_fma_f32 v[34:35], v[34:35], v[130:131], v[194:195]
	v_pk_fma_f32 v[36:37], v[36:37], v[132:133], v[196:197]
	v_mul_f32_e32 v250, v46, v46
	v_mul_f32_e32 v251, v38, v38
	v_fmac_f32_e32 v250, v47, v47
	v_fmac_f32_e32 v251, v39, v39
	v_fmac_f32_e32 v250, v48, v48
	v_fmac_f32_e32 v251, v40, v40
	v_fmac_f32_e32 v250, v49, v49
	v_fmac_f32_e32 v251, v41, v41
	v_fmac_f32_e32 v250, v42, v42
	v_fmac_f32_e32 v251, v34, v34
	v_fmac_f32_e32 v250, v43, v43
	v_fmac_f32_e32 v251, v35, v35
	v_fmac_f32_e32 v250, v44, v44
	v_fmac_f32_e32 v251, v36, v36
	v_fmac_f32_e32 v250, v45, v45
	v_fmac_f32_e32 v251, v37, v37
	v_add_f32_e32 v250, v250, v251
	ds_bpermute_b32 v251, v200, v250
	s_waitcnt lgkmcnt(0)
	v_add_f32_e32 v250, v250, v251
	ds_bpermute_b32 v251, v201, v250
	s_waitcnt lgkmcnt(0)
	v_add_f32_e32 v250, v250, v251
	v_cvt_f64_f32_e32 v[180:181], v250
	s_nop 0
	v_add_f64 v[180:181], v[180:181], s[44:45]
	s_and_saveexec_b64 s[42:43], s[38:39]
	global_atomic_add_f64 v[198:199], v[180:181], off offset:1152
	s_mov_b64 exec, s[42:43]
	s_nop 1
	s_waitcnt vmcnt(7)
	v_pk_fma_f32 v[30:31], v[30:31], v[142:143], v[230:231]
	v_pk_fma_f32 v[32:33], v[32:33], v[144:145], v[232:233]
	v_pk_fma_f32 v[26:27], v[26:27], v[138:139], v[234:235]
	v_pk_fma_f32 v[28:29], v[28:29], v[140:141], v[236:237]
	v_pk_fma_f32 v[22:23], v[22:23], v[134:135], v[238:239]
	v_pk_fma_f32 v[24:25], v[24:25], v[136:137], v[240:241]
	v_pk_fma_f32 v[18:19], v[18:19], v[130:131], v[242:243]
	v_pk_fma_f32 v[20:21], v[20:21], v[132:133], v[244:245]
	v_mul_f32_e32 v250, v30, v30
	v_mul_f32_e32 v251, v22, v22
	v_fmac_f32_e32 v250, v31, v31
	v_fmac_f32_e32 v251, v23, v23
	v_fmac_f32_e32 v250, v32, v32
	v_fmac_f32_e32 v251, v24, v24
	v_fmac_f32_e32 v250, v33, v33
	v_fmac_f32_e32 v251, v25, v25
	v_fmac_f32_e32 v250, v26, v26
	v_fmac_f32_e32 v251, v18, v18
	v_fmac_f32_e32 v250, v27, v27
	v_fmac_f32_e32 v251, v19, v19
	v_fmac_f32_e32 v250, v28, v28
	v_fmac_f32_e32 v251, v20, v20
	v_fmac_f32_e32 v250, v29, v29
	v_fmac_f32_e32 v251, v21, v21
	v_add_f32_e32 v250, v250, v251
	ds_bpermute_b32 v251, v200, v250
	s_waitcnt lgkmcnt(0)
	v_add_f32_e32 v250, v250, v251
	ds_bpermute_b32 v251, v201, v250
	s_waitcnt lgkmcnt(0)
	v_add_f32_e32 v250, v250, v251
	v_cvt_f64_f32_e32 v[180:181], v250
	s_nop 0
	v_add_f64 v[180:181], v[180:181], s[44:45]
	s_and_saveexec_b64 s[42:43], s[38:39]
	global_atomic_add_f64 v[198:199], v[180:181], off offset:1280
	s_mov_b64 exec, s[42:43]
	s_nop 1
	s_waitcnt vmcnt(3)
	v_pk_fma_f32 v[14:15], v[14:15], v[142:143], v[146:147]
	v_pk_fma_f32 v[16:17], v[16:17], v[144:145], v[148:149]
	v_pk_fma_f32 v[10:11], v[10:11], v[138:139], v[150:151]
	v_pk_fma_f32 v[12:13], v[12:13], v[140:141], v[152:153]
	v_pk_fma_f32 v[6:7], v[6:7], v[134:135], v[176:177]
	v_pk_fma_f32 v[8:9], v[8:9], v[136:137], v[178:179]
	v_pk_fma_f32 v[2:3], v[2:3], v[130:131], v[202:203]
	v_pk_fma_f32 v[4:5], v[4:5], v[132:133], v[204:205]
	v_mul_f32_e32 v250, v14, v14
	v_mul_f32_e32 v251, v6, v6
	v_fmac_f32_e32 v250, v15, v15
	v_fmac_f32_e32 v251, v7, v7
	v_fmac_f32_e32 v250, v16, v16
	v_fmac_f32_e32 v251, v8, v8
	v_fmac_f32_e32 v250, v17, v17
	v_fmac_f32_e32 v251, v9, v9
	v_fmac_f32_e32 v250, v10, v10
	v_fmac_f32_e32 v251, v2, v2
	v_fmac_f32_e32 v250, v11, v11
	v_fmac_f32_e32 v251, v3, v3
	v_fmac_f32_e32 v250, v12, v12
	v_fmac_f32_e32 v251, v4, v4
	v_fmac_f32_e32 v250, v13, v13
	v_fmac_f32_e32 v251, v5, v5
	v_add_f32_e32 v250, v250, v251
	ds_bpermute_b32 v251, v200, v250
	s_waitcnt lgkmcnt(0)
	v_add_f32_e32 v250, v250, v251
	ds_bpermute_b32 v251, v201, v250
	s_waitcnt lgkmcnt(0)
	v_add_f32_e32 v250, v250, v251
	v_cvt_f64_f32_e32 v[180:181], v250
	s_nop 0
	v_add_f64 v[180:181], v[180:181], s[44:45]
	s_and_saveexec_b64 s[42:43], s[38:39]
	global_atomic_add_f64 v[198:199], v[180:181], off offset:1408
	s_mov_b64 exec, s[42:43]
	s_nop 1
	s_mov_b32 s0, 0
	s_mov_b32 s1, 0x42c00000
	s_mov_b32 s6, 0
.Lfn_spin:
	s_and_saveexec_b64 s[42:43], s[38:39]
	global_load_dwordx2 v[230:231], v[198:199], off sc1
	global_load_dwordx2 v[232:233], v[198:199], off offset:128 sc1
	global_load_dwordx2 v[234:235], v[198:199], off offset:256 sc1
	global_load_dwordx2 v[236:237], v[198:199], off offset:384 sc1
	global_load_dwordx2 v[238:239], v[198:199], off offset:1024 sc1
	global_load_dwordx2 v[240:241], v[198:199], off offset:1152 sc1
	global_load_dwordx2 v[242:243], v[198:199], off offset:1280 sc1
	global_load_dwordx2 v[244:245], v[198:199], off offset:1408 sc1
	s_waitcnt vmcnt(0)
	v_min_f64 v[250:251], v[230:231], v[232:233]
	v_min_f64 v[250:251], v[250:251], v[234:235]
	v_min_f64 v[250:251], v[250:251], v[236:237]
	v_min_f64 v[250:251], v[250:251], v[238:239]
	v_min_f64 v[250:251], v[250:251], v[240:241]
	v_min_f64 v[250:251], v[250:251], v[242:243]
	v_min_f64 v[250:251], v[250:251], v[244:245]
	s_nop 1
	v_cmp_gt_f64_e32 vcc, s[0:1], v[250:251]
	s_mov_b64 exec, s[42:43]
	s_cbranch_vccz .Lfn_go
	s_add_i32 s6, s6, 1
	s_cmp_lt_u32 s6, 0x1000
	s_cbranch_scc0 .Lfn_go
	s_sleep 1
	s_branch .Lfn_spin
.Lfn_go:
	v_add_f64 v[230:231], v[230:231], -s[0:1]
	v_add_f64 v[232:233], v[232:233], -s[0:1]
	v_add_f64 v[234:235], v[234:235], -s[0:1]
	v_add_f64 v[236:237], v[236:237], -s[0:1]
	v_add_f64 v[238:239], v[238:239], -s[0:1]
	v_add_f64 v[240:241], v[240:241], -s[0:1]
	v_add_f64 v[242:243], v[242:243], -s[0:1]
	v_add_f64 v[244:245], v[244:245], -s[0:1]
	v_cvt_f32_f64_e32 v230, v[230:231]
	v_cvt_f32_f64_e32 v232, v[232:233]
	v_cvt_f32_f64_e32 v234, v[234:235]
	v_cvt_f32_f64_e32 v236, v[236:237]
	v_cvt_f32_f64_e32 v238, v[238:239]
	v_cvt_f32_f64_e32 v240, v[240:241]
	v_cvt_f32_f64_e32 v242, v[242:243]
	v_cvt_f32_f64_e32 v244, v[244:245]
	v_readlane_b32 s0, v253, 60
	v_readlane_b32 s1, v253, 61
	v_lshl_or_b32 v250, s76, 8, v228
	v_mov_b32_e32 v251, 0
	s_nop 2
	v_lshl_add_u64 v[250:251], v[250:251], 2, s[0:1]
	global_load_dwordx4 v[182:185], v[250:251], off
	global_load_dwordx4 v[186:189], v[250:251], off offset:16
	global_load_dwordx4 v[190:193], v[250:251], off offset:128
	global_load_dwordx4 v[194:197], v[250:251], off offset:144
	v_and_b32_e32 v0, 15, v154
	v_lshlrev_b32_e32 v0, 2, v0
	s_mov_b64 exec, s[42:43]
	s_waitcnt vmcnt(0)
	ds_bpermute_b32 v230, v0, v230
	ds_bpermute_b32 v232, v0, v232
	ds_bpermute_b32 v234, v0, v234
	ds_bpermute_b32 v236, v0, v236
	ds_bpermute_b32 v238, v0, v238
	ds_bpermute_b32 v240, v0, v240
	ds_bpermute_b32 v242, v0, v242
	ds_bpermute_b32 v244, v0, v244
	s_waitcnt lgkmcnt(0)
	v_fmamk_f32 v230, v230, 0x3a000000, v207
	s_nop 0
	v_rsq_f32_e32 v230, v230
	s_nop 0
	v_pk_mul_f32 v[126:127], v[126:127], v[230:231] op_sel_hi:[1,0]
	v_pk_mul_f32 v[126:127], v[182:183], v[126:127]
	v_pk_mul_f32 v[128:129], v[128:129], v[230:231] op_sel_hi:[1,0]
	v_pk_mul_f32 v[128:129], v[184:185], v[128:129]
	v_pk_mul_f32 v[122:123], v[122:123], v[230:231] op_sel_hi:[1,0]
	v_pk_mul_f32 v[122:123], v[186:187], v[122:123]
	v_pk_mul_f32 v[124:125], v[124:125], v[230:231] op_sel_hi:[1,0]
	v_pk_mul_f32 v[124:125], v[188:189], v[124:125]
	v_pk_mul_f32 v[118:119], v[118:119], v[230:231] op_sel_hi:[1,0]
	v_pk_mul_f32 v[118:119], v[190:191], v[118:119]
	v_pk_mul_f32 v[120:121], v[120:121], v[230:231] op_sel_hi:[1,0]
	v_pk_mul_f32 v[120:121], v[192:193], v[120:121]
	v_pk_mul_f32 v[114:115], v[114:115], v[230:231] op_sel_hi:[1,0]
	v_pk_mul_f32 v[114:115], v[194:195], v[114:115]
	v_pk_mul_f32 v[116:117], v[116:117], v[230:231] op_sel_hi:[1,0]
	v_pk_mul_f32 v[116:117], v[196:197], v[116:117]
	global_store_dwordx4 v[248:249], v[126:129], off
	global_store_dwordx4 v[248:249], v[122:125], off offset:16
	global_store_dwordx4 v[248:249], v[118:121], off offset:128
	global_store_dwordx4 v[248:249], v[114:117], off offset:144
	v_fmamk_f32 v232, v232, 0x3a000000, v207
	s_nop 0
	v_rsq_f32_e32 v232, v232
	s_nop 0
	v_pk_mul_f32 v[110:111], v[110:111], v[232:233] op_sel_hi:[1,0]
	v_pk_mul_f32 v[110:111], v[182:183], v[110:111]
	v_pk_mul_f32 v[112:113], v[112:113], v[232:233] op_sel_hi:[1,0]
	v_pk_mul_f32 v[112:113], v[184:185], v[112:113]
	v_pk_mul_f32 v[106:107], v[106:107], v[232:233] op_sel_hi:[1,0]
	v_pk_mul_f32 v[106:107], v[186:187], v[106:107]
	v_pk_mul_f32 v[108:109], v[108:109], v[232:233] op_sel_hi:[1,0]
	v_pk_mul_f32 v[108:109], v[188:189], v[108:109]
	v_pk_mul_f32 v[102:103], v[102:103], v[232:233] op_sel_hi:[1,0]
	v_pk_mul_f32 v[102:103], v[190:191], v[102:103]
	v_pk_mul_f32 v[104:105], v[104:105], v[232:233] op_sel_hi:[1,0]
	v_pk_mul_f32 v[104:105], v[192:193], v[104:105]
	v_pk_mul_f32 v[98:99], v[98:99], v[232:233] op_sel_hi:[1,0]
	v_pk_mul_f32 v[98:99], v[194:195], v[98:99]
	v_pk_mul_f32 v[100:101], v[100:101], v[232:233] op_sel_hi:[1,0]
	v_pk_mul_f32 v[100:101], v[196:197], v[100:101]
	s_mov_b64 s[42:43], 0x20000
	v_lshl_add_u64 v[180:181], v[248:249], 0, s[42:43]
	global_store_dwordx4 v[180:181], v[110:113], off
	global_store_dwordx4 v[180:181], v[106:109], off offset:16
	global_store_dwordx4 v[180:181], v[102:105], off offset:128
	global_store_dwordx4 v[180:181], v[98:101], off offset:144
	v_fmamk_f32 v234, v234, 0x3a000000, v207
	s_nop 0
	v_rsq_f32_e32 v234, v234
	s_nop 0
	v_pk_mul_f32 v[94:95], v[94:95], v[234:235] op_sel_hi:[1,0]
	v_pk_mul_f32 v[94:95], v[182:183], v[94:95]
	v_pk_mul_f32 v[96:97], v[96:97], v[234:235] op_sel_hi:[1,0]
	v_pk_mul_f32 v[96:97], v[184:185], v[96:97]
	v_pk_mul_f32 v[90:91], v[90:91], v[234:235] op_sel_hi:[1,0]
	v_pk_mul_f32 v[90:91], v[186:187], v[90:91]
	v_pk_mul_f32 v[92:93], v[92:93], v[234:235] op_sel_hi:[1,0]
	v_pk_mul_f32 v[92:93], v[188:189], v[92:93]
	v_pk_mul_f32 v[86:87], v[86:87], v[234:235] op_sel_hi:[1,0]
	v_pk_mul_f32 v[86:87], v[190:191], v[86:87]
	v_pk_mul_f32 v[88:89], v[88:89], v[234:235] op_sel_hi:[1,0]
	v_pk_mul_f32 v[88:89], v[192:193], v[88:89]
	v_pk_mul_f32 v[82:83], v[82:83], v[234:235] op_sel_hi:[1,0]
	v_pk_mul_f32 v[82:83], v[194:195], v[82:83]
	v_pk_mul_f32 v[84:85], v[84:85], v[234:235] op_sel_hi:[1,0]
	v_pk_mul_f32 v[84:85], v[196:197], v[84:85]
	s_mov_b64 s[42:43], 0x40000
	v_lshl_add_u64 v[180:181], v[248:249], 0, s[42:43]
	global_store_dwordx4 v[180:181], v[94:97], off
	global_store_dwordx4 v[180:181], v[90:93], off offset:16
	global_store_dwordx4 v[180:181], v[86:89], off offset:128
	global_store_dwordx4 v[180:181], v[82:85], off offset:144
	v_fmamk_f32 v236, v236, 0x3a000000, v207
	s_nop 0
	v_rsq_f32_e32 v236, v236
	s_nop 0
	v_pk_mul_f32 v[78:79], v[78:79], v[236:237] op_sel_hi:[1,0]
	v_pk_mul_f32 v[78:79], v[182:183], v[78:79]
	v_pk_mul_f32 v[80:81], v[80:81], v[236:237] op_sel_hi:[1,0]
	v_pk_mul_f32 v[80:81], v[184:185], v[80:81]
	v_pk_mul_f32 v[74:75], v[74:75], v[236:237] op_sel_hi:[1,0]
	v_pk_mul_f32 v[74:75], v[186:187], v[74:75]
	v_pk_mul_f32 v[76:77], v[76:77], v[236:237] op_sel_hi:[1,0]
	v_pk_mul_f32 v[76:77], v[188:189], v[76:77]
	v_pk_mul_f32 v[70:71], v[70:71], v[236:237] op_sel_hi:[1,0]
	v_pk_mul_f32 v[70:71], v[190:191], v[70:71]
	v_pk_mul_f32 v[72:73], v[72:73], v[236:237] op_sel_hi:[1,0]
	v_pk_mul_f32 v[72:73], v[192:193], v[72:73]
	v_pk_mul_f32 v[66:67], v[66:67], v[236:237] op_sel_hi:[1,0]
	v_pk_mul_f32 v[66:67], v[194:195], v[66:67]
	v_pk_mul_f32 v[68:69], v[68:69], v[236:237] op_sel_hi:[1,0]
	v_pk_mul_f32 v[68:69], v[196:197], v[68:69]
	s_mov_b64 s[42:43], 0x60000
	v_lshl_add_u64 v[180:181], v[248:249], 0, s[42:43]
	global_store_dwordx4 v[180:181], v[78:81], off
	global_store_dwordx4 v[180:181], v[74:77], off offset:16
	global_store_dwordx4 v[180:181], v[70:73], off offset:128
	global_store_dwordx4 v[180:181], v[66:69], off offset:144
	v_fmamk_f32 v238, v238, 0x3a000000, v207
	s_nop 0
	v_rsq_f32_e32 v238, v238
	s_nop 0
	v_pk_mul_f32 v[62:63], v[62:63], v[238:239] op_sel_hi:[1,0]
	v_pk_mul_f32 v[62:63], v[182:183], v[62:63]
	v_pk_mul_f32 v[64:65], v[64:65], v[238:239] op_sel_hi:[1,0]
	v_pk_mul_f32 v[64:65], v[184:185], v[64:65]
	v_pk_mul_f32 v[58:59], v[58:59], v[238:239] op_sel_hi:[1,0]
	v_pk_mul_f32 v[58:59], v[186:187], v[58:59]
	v_pk_mul_f32 v[60:61], v[60:61], v[238:239] op_sel_hi:[1,0]
	v_pk_mul_f32 v[60:61], v[188:189], v[60:61]
	v_pk_mul_f32 v[54:55], v[54:55], v[238:239] op_sel_hi:[1,0]
	v_pk_mul_f32 v[54:55], v[190:191], v[54:55]
	v_pk_mul_f32 v[56:57], v[56:57], v[238:239] op_sel_hi:[1,0]
	v_pk_mul_f32 v[56:57], v[192:193], v[56:57]
	v_pk_mul_f32 v[50:51], v[50:51], v[238:239] op_sel_hi:[1,0]
	v_pk_mul_f32 v[50:51], v[194:195], v[50:51]
	v_pk_mul_f32 v[52:53], v[52:53], v[238:239] op_sel_hi:[1,0]
	v_pk_mul_f32 v[52:53], v[196:197], v[52:53]
	s_mov_b64 s[42:43], 0x100000
	v_lshl_add_u64 v[180:181], v[248:249], 0, s[42:43]
	global_store_dwordx4 v[180:181], v[62:65], off
	global_store_dwordx4 v[180:181], v[58:61], off offset:16
	global_store_dwordx4 v[180:181], v[54:57], off offset:128
	global_store_dwordx4 v[180:181], v[50:53], off offset:144
	v_fmamk_f32 v240, v240, 0x3a000000, v207
	s_nop 0
	v_rsq_f32_e32 v240, v240
	s_nop 0
	v_pk_mul_f32 v[46:47], v[46:47], v[240:241] op_sel_hi:[1,0]
	v_pk_mul_f32 v[46:47], v[182:183], v[46:47]
	v_pk_mul_f32 v[48:49], v[48:49], v[240:241] op_sel_hi:[1,0]
	v_pk_mul_f32 v[48:49], v[184:185], v[48:49]
	v_pk_mul_f32 v[42:43], v[42:43], v[240:241] op_sel_hi:[1,0]
	v_pk_mul_f32 v[42:43], v[186:187], v[42:43]
	v_pk_mul_f32 v[44:45], v[44:45], v[240:241] op_sel_hi:[1,0]
	v_pk_mul_f32 v[44:45], v[188:189], v[44:45]
	v_pk_mul_f32 v[38:39], v[38:39], v[240:241] op_sel_hi:[1,0]
	v_pk_mul_f32 v[38:39], v[190:191], v[38:39]
	v_pk_mul_f32 v[40:41], v[40:41], v[240:241] op_sel_hi:[1,0]
	v_pk_mul_f32 v[40:41], v[192:193], v[40:41]
	v_pk_mul_f32 v[34:35], v[34:35], v[240:241] op_sel_hi:[1,0]
	v_pk_mul_f32 v[34:35], v[194:195], v[34:35]
	v_pk_mul_f32 v[36:37], v[36:37], v[240:241] op_sel_hi:[1,0]
	v_pk_mul_f32 v[36:37], v[196:197], v[36:37]
	s_mov_b64 s[42:43], 0x120000
	v_lshl_add_u64 v[180:181], v[248:249], 0, s[42:43]
	global_store_dwordx4 v[180:181], v[46:49], off
	global_store_dwordx4 v[180:181], v[42:45], off offset:16
	global_store_dwordx4 v[180:181], v[38:41], off offset:128
	global_store_dwordx4 v[180:181], v[34:37], off offset:144
	v_fmamk_f32 v242, v242, 0x3a000000, v207
	s_nop 0
	v_rsq_f32_e32 v242, v242
	s_nop 0
	v_pk_mul_f32 v[30:31], v[30:31], v[242:243] op_sel_hi:[1,0]
	v_pk_mul_f32 v[30:31], v[182:183], v[30:31]
	v_pk_mul_f32 v[32:33], v[32:33], v[242:243] op_sel_hi:[1,0]
	v_pk_mul_f32 v[32:33], v[184:185], v[32:33]
	v_pk_mul_f32 v[26:27], v[26:27], v[242:243] op_sel_hi:[1,0]
	v_pk_mul_f32 v[26:27], v[186:187], v[26:27]
	v_pk_mul_f32 v[28:29], v[28:29], v[242:243] op_sel_hi:[1,0]
	v_pk_mul_f32 v[28:29], v[188:189], v[28:29]
	v_pk_mul_f32 v[22:23], v[22:23], v[242:243] op_sel_hi:[1,0]
	v_pk_mul_f32 v[22:23], v[190:191], v[22:23]
	v_pk_mul_f32 v[24:25], v[24:25], v[242:243] op_sel_hi:[1,0]
	v_pk_mul_f32 v[24:25], v[192:193], v[24:25]
	v_pk_mul_f32 v[18:19], v[18:19], v[242:243] op_sel_hi:[1,0]
	v_pk_mul_f32 v[18:19], v[194:195], v[18:19]
	v_pk_mul_f32 v[20:21], v[20:21], v[242:243] op_sel_hi:[1,0]
	v_pk_mul_f32 v[20:21], v[196:197], v[20:21]
	s_mov_b64 s[42:43], 0x140000
	v_lshl_add_u64 v[180:181], v[248:249], 0, s[42:43]
	global_store_dwordx4 v[180:181], v[30:33], off
	global_store_dwordx4 v[180:181], v[26:29], off offset:16
	global_store_dwordx4 v[180:181], v[22:25], off offset:128
	global_store_dwordx4 v[180:181], v[18:21], off offset:144
	v_fmamk_f32 v244, v244, 0x3a000000, v207
	s_nop 0
	v_rsq_f32_e32 v244, v244
	s_nop 0
	v_pk_mul_f32 v[14:15], v[14:15], v[244:245] op_sel_hi:[1,0]
	v_pk_mul_f32 v[14:15], v[182:183], v[14:15]
	v_pk_mul_f32 v[16:17], v[16:17], v[244:245] op_sel_hi:[1,0]
	v_pk_mul_f32 v[16:17], v[184:185], v[16:17]
	v_pk_mul_f32 v[10:11], v[10:11], v[244:245] op_sel_hi:[1,0]
	v_pk_mul_f32 v[10:11], v[186:187], v[10:11]
	v_pk_mul_f32 v[12:13], v[12:13], v[244:245] op_sel_hi:[1,0]
	v_pk_mul_f32 v[12:13], v[188:189], v[12:13]
	v_pk_mul_f32 v[6:7], v[6:7], v[244:245] op_sel_hi:[1,0]
	v_pk_mul_f32 v[6:7], v[190:191], v[6:7]
	v_pk_mul_f32 v[8:9], v[8:9], v[244:245] op_sel_hi:[1,0]
	v_pk_mul_f32 v[8:9], v[192:193], v[8:9]
	v_pk_mul_f32 v[2:3], v[2:3], v[244:245] op_sel_hi:[1,0]
	v_pk_mul_f32 v[2:3], v[194:195], v[2:3]
	v_pk_mul_f32 v[4:5], v[4:5], v[244:245] op_sel_hi:[1,0]
	v_pk_mul_f32 v[4:5], v[196:197], v[4:5]
	s_mov_b64 s[42:43], 0x160000
	v_lshl_add_u64 v[180:181], v[248:249], 0, s[42:43]
	global_store_dwordx4 v[180:181], v[14:17], off
	global_store_dwordx4 v[180:181], v[10:13], off offset:16
	global_store_dwordx4 v[180:181], v[6:9], off offset:128
	global_store_dwordx4 v[180:181], v[2:5], off offset:144
	s_branch .LBB0_487

.LBB0_615:
.LBB0_616:
	s_add_i32 s12, s12, 1
	s_mov_b64 s[0:1], -1
	s_cmp_eq_u32 s12, 17
	s_cbranch_scc1 .LBB0_186
	s_cmp_ge_i32 s12, s14
	s_cbranch_scc1 .LBB0_186
